# split-phase grid barrier 5: the out-projection's first 8 K-tiles read only MIX's attention half (P2), so non-leader workgroups arrive only and complete the wait inside the K-loop before K-tile 8 is pr
# speedup vs baseline: 1.0186x; 1.0112x over previous
; __device__ __forceinline__ unsigned xb_ld(unsigned* p)              { return __hip_atomic_load(p, __ATOMIC_RELAXED, __HIP_MEMORY_SCOPE_AGENT); }
; __device__ __forceinline__ unsigned xb_add(unsigned* p, unsigned v) { return __hip_atomic_fetch_add(p, v, __ATOMIC_RELAXED, __HIP_MEMORY_SCOPE_AGENT); }
; #define XB_SPIN(cond, bar) do { unsigned _sp = 0; while (cond) { __builtin_amdgcn_s_sleep(1); \
;     if ((++_sp & 255u) == 0u) { if (xb_ld(&(bar)[XB_TMO])) break; if (_sp > XB_SPIN_CAP) { atomicAdd(&(bar)[XB_TMO], 1u); break; } } } } while (0)
; __device__ __forceinline__ void xcd_barrier(const XcdBarrier& b) {
;     ...
;         const unsigned old = xb_add(&bar[XB_XSUB(b.x)], 1u);
;         const unsigned gen = old / nloc;
;         if (old + 1u == (gen + 1u) * nloc) {
;             __builtin_amdgcn_fence(__ATOMIC_RELEASE, "agent");
;             asm volatile("s_waitcnt vmcnt(0)" ::: "memory");
;             const unsigned og = xb_add(&bar[XB_TOP], 1u);
;             const unsigned tg = og / nx;
;             if (og + 1u == (tg + 1u) * nx) xb_add(&bar[XB_TOPGEN], 1u);
;             else XB_SPIN(xb_ld(&bar[XB_TOPGEN]) == tg, bar);
;             __builtin_amdgcn_fence(__ATOMIC_ACQUIRE, "agent");
;             xb_add(&bar[XB_XGEN(b.x)], 1u);
;             asm volatile("s_waitcnt vmcnt(0)" ::: "memory");
;         } else {
;             XB_SPIN(xb_ld(&bar[XB_XGEN(b.x)]) == gen, bar);
;             __builtin_amdgcn_fence(__ATOMIC_ACQUIRE, "agent");
.LBB0_804:
	s_or_b64 exec, exec, s[8:9]
	v_cvt_f32_u32_e32 v4, v2
	s_waitcnt vmcnt(0)
	v_readfirstlane_b32 s3, v3
	v_sub_u32_e32 v3, 0, v2
	v_rcp_iflag_f32_e32 v4, v4
	v_add_u32_e32 v5, s3, v1
	v_mul_f32_e32 v4, 0x4f7ffffe, v4
	v_cvt_u32_f32_e32 v4, v4
	v_mul_lo_u32 v1, v3, v4
	v_mul_hi_u32 v1, v4, v1
	v_add_u32_e32 v1, v4, v1
	v_mul_hi_u32 v1, v5, v1
	v_mul_lo_u32 v3, v1, v2
	v_sub_u32_e32 v3, v5, v3
	v_add_u32_e32 v4, 1, v1
	v_cmp_ge_u32_e32 vcc, v3, v2
	s_nop 1
	v_cndmask_b32_e32 v1, v1, v4, vcc
	v_sub_u32_e32 v4, v3, v2
	v_cndmask_b32_e32 v3, v3, v4, vcc
	v_add_u32_e32 v4, 1, v1
	v_cmp_ge_u32_e32 vcc, v3, v2
	v_add_u32_e32 v3, 1, v5
	s_nop 0
	v_cndmask_b32_e32 v1, v1, v4, vcc
	v_mul_lo_u32 v4, v2, v1
	v_add_u32_e32 v2, v4, v2
	v_cmp_ne_u32_e32 vcc, v3, v2
	s_and_saveexec_b64 s[6:7], vcc
	s_xor_b64 s[6:7], exec, s[6:7]
	s_cbranch_execz .LBB0_818
	s_cmp_lg_u32 s100, 0
	s_cbranch_scc1 .Lsp5_norm
	v_mov_b32_e32 v248, v1
	s_mov_b32 s101, 0x5555
	s_branch .LBB0_818

; __device__ __forceinline__ unsigned xb_ld(unsigned* p)              { return __hip_atomic_load(p, __ATOMIC_RELAXED, __HIP_MEMORY_SCOPE_AGENT); }
; #define XB_SPIN(cond, bar) do { unsigned _sp = 0; while (cond) { __builtin_amdgcn_s_sleep(1); \
;     if ((++_sp & 255u) == 0u) { if (xb_ld(&(bar)[XB_TMO])) break; if (_sp > XB_SPIN_CAP) { atomicAdd(&(bar)[XB_TMO], 1u); break; } } } } while (0)
; __device__ __forceinline__ void xcd_barrier(const XcdBarrier& b) {
;     ...
;             XB_SPIN(xb_ld(&bar[XB_XGEN(b.x)]) == gen, bar);
;             __builtin_amdgcn_fence(__ATOMIC_ACQUIRE, "agent");
.Lsp5_h:
	s_cmp_eq_u32 s58, 0
	s_cbranch_scc0 .Lsp5_h2
	s_mov_b64 exec, 1
	s_lshl_b32 s98, s33, 8
	s_add_u32 s98, s98, 0x82400
	v_mov_b32_e32 v246, s98
	global_load_dword v247, v246, s[68:69] sc1
	s_mov_b64 exec, -1
	s_branch .Lsp5_back
.Lsp5_h2:
	s_cmp_eq_u32 s58, 2
	s_cbranch_scc0 .Lsp5_back
	s_mov_b64 exec, 1
	s_mov_b32 s98, 0x40000

; __device__ __forceinline__ unsigned xb_ld(unsigned* p)              { return __hip_atomic_load(p, __ATOMIC_RELAXED, __HIP_MEMORY_SCOPE_AGENT); }
; #define XB_SPIN(cond, bar) do { unsigned _sp = 0; while (cond) { __builtin_amdgcn_s_sleep(1); \
;     if ((++_sp & 255u) == 0u) { if (xb_ld(&(bar)[XB_TMO])) break; if (_sp > XB_SPIN_CAP) { atomicAdd(&(bar)[XB_TMO], 1u); break; } } } } while (0)
; __device__ __forceinline__ void xcd_barrier(const XcdBarrier& b) {
;     ...
;             XB_SPIN(xb_ld(&bar[XB_XGEN(b.x)]) == gen, bar);
;             __builtin_amdgcn_fence(__ATOMIC_ACQUIRE, "agent");
.Lsp5_ok:
	buffer_inv sc1
	s_mov_b32 s101, 0
	s_mov_b64 exec, -1
	s_branch .Lsp5_back

;     __host__ __device__ bool next(int i, Unit& u) const { return at((long)i * G + c, u); }
;     __host__ __device__ bool next(int i, Unit& u) const { if (i != 0 || c >= cnt) return false; u.pm = pm0 + c / nN; u.pn = c % nN; u.k0 = 0; u.nt = ntk; return true; }
; #define PG8_STAGE(bufoff, gbase, voff) do { _Pragma("unroll") for (int _i = 0; _i < 2; ++_i) \
;         __builtin_amdgcn_global_load_lds((const unsigned*)((const char*)(gbase) + (voff)[_i]), (PG8_LAS unsigned*)(lds + (bufoff) + ldsw + _i * 8192), 16, 0, 0); } while (0)
; #define PG8_STAGEA(bufoff, gbase, voff) do { _Pragma("unroll") for (int _i = 0; _i < 2; ++_i) \
;         __builtin_amdgcn_global_load_lds((const unsigned*)((const char*)(gbase) + (voff)[_i]), (PG8_LAS unsigned*)(lds + (bufoff) + ldsw + _i * 8192), 16, 0, AUXA); } while (0)
; #define PG8_LDA(dst, b, h) do { _Pragma("unroll") for (int m = 0; m < 4; ++m) _Pragma("unroll") for (int k = 0; k < 2; ++k) dst[m][k] = *(const PG8_LAS bf16x8*)(lds + PG8_SA(b, h) + aoff + m * 2048 + k * 1024); } while (0)
; #define PG8_WAIT_V(n) asm volatile("s_waitcnt vmcnt(" #n ")" ::: "memory")
;     ...
;         const bool has_next = S.next(ui + 1, nxt);
;         const char* nA = has_next ? (const char*)g.A + (size_t)nxt.pm * tstep + (size_t)nxt.k0 * (BK * 2) : cA; const char* nB = has_next ? (const char*)g.Bt + (size_t)nxt.pn * tstep + (size_t)nxt.k0 * (BK * 2) : cB;
;         const int nt = cur.nt;
;         for (int t = 0; t < nt; t += 2) {
;             const bool last = (t == nt - 2);
;             const char* a1 = cA + (size_t)(t + 1) * kstep;
;             const char* a2 = last ? nA : cA + (size_t)(t + 2) * kstep; const char* b2 = last ? nB : cB + (size_t)(t + 2) * kstep;
;             const char* a3 = a2 + kstep; const char* b3 = b2 + kstep;
;             if (last && has_next) S.a_ready(nxt);
;             if constexpr (SP2) {
;             PG8_LDB(B0, 0, 0); PG8_LDB(B1, 0, 1); PG8_SCHED; PG8_LDA(At, 0, 0); PG8_STAGEA(PG8_SA(1, 1), a1 + hstep, voffA);
;             PG8_WAIT_V(8); PG8_WAIT_L(0); PG8_BAR; PG8_MMA(0, 0, At, B0); PG8_MMA(0, 1, At, B1); PG8_BAR; PG8_SCHED;
;             PG8_LDA(At, 0, 1); PG8_STAGE(PG8_SB(0, 0), b2, voffB); PG8_STAGE(PG8_SB(0, 1), b2 + hstepB, voffB); PG8_STAGEA(PG8_SA(0, 0), a2, voffA);
;             PG8_WAIT_V(8); PG8_WAIT_L(0); PG8_BAR; PG8_MMA(1, 0, At, B0); PG8_MMA(1, 1, At, B1); PG8_BAR; PG8_SCHED;
.Lsprio_3:
.LBB0_854:
	ds_read_b128 v[142:145], v151
	ds_read_b128 v[154:157], v151 offset:1024
	ds_read_b128 v[158:161], v151 offset:2048
	ds_read_b128 v[162:165], v151 offset:3072
	ds_read_b128 v[166:169], v152
	ds_read_b128 v[170:173], v152 offset:1024
	ds_read_b128 v[176:179], v152 offset:2048
	ds_read_b128 v[180:183], v152 offset:3072
	s_add_u32 s36, s34, 0xfffc0080
	s_addc_u32 s37, s35, -1
	s_cmp_eq_u32 s58, 12
	s_cselect_b32 s39, s15, s37
	s_cselect_b32 s38, s25, s36
	s_cselect_b32 s37, s23, s57
	s_cselect_b32 s36, s31, s56
	s_cmp_eq_u32 s101, 0x5555
	s_cbranch_scc1 .Lsp5_h
.Lsp5_back:
	v_lshl_add_u64 v[206:207], s[34:35], 0, v[136:137]
	s_add_i32 m0, s40, 0xc000
	ds_read_b128 v[184:187], v153
	ds_read_b128 v[188:191], v153 offset:1024
	ds_read_b128 v[192:195], v153 offset:2048
	ds_read_b128 v[196:199], v153 offset:3072
	ds_read_b128 v[202:205], v153 offset:4096
	ds_read_b128 v[210:213], v153 offset:5120
	ds_read_b128 v[214:217], v153 offset:6144
	ds_read_b128 v[218:221], v153 offset:7168
	global_load_lds_dwordx4 v[206:207], off
	v_lshl_add_u64 v[206:207], s[34:35], 0, v[138:139]
	s_add_i32 m0, s40, 0xe000
	s_nop 0
	global_load_lds_dwordx4 v[206:207], off
	s_waitcnt vmcnt(8)
	s_waitcnt lgkmcnt(0)
	s_barrier
	s_waitcnt lgkmcnt(0)
	v_mfma_f32_16x16x32_bf16 v[124:127], v[142:145], v[184:187], v[124:127]
	v_mfma_f32_16x16x32_bf16 v[120:123], v[158:161], v[184:187], v[120:123]
	v_mfma_f32_16x16x32_bf16 v[108:111], v[142:145], v[192:195], v[108:111]
	v_mfma_f32_16x16x32_bf16 v[104:107], v[158:161], v[192:195], v[104:107]
	v_mfma_f32_16x16x32_bf16 v[92:95], v[142:145], v[202:205], v[92:95]
	v_mfma_f32_16x16x32_bf16 v[88:91], v[158:161], v[202:205], v[88:91]
	v_mfma_f32_16x16x32_bf16 v[76:79], v[142:145], v[214:217], v[76:79]
	v_mfma_f32_16x16x32_bf16 v[72:75], v[158:161], v[214:217], v[72:75]
	v_mfma_f32_16x16x32_bf16 v[124:127], v[154:157], v[188:191], v[124:127]
	v_mfma_f32_16x16x32_bf16 v[120:123], v[162:165], v[188:191], v[120:123]
	v_mfma_f32_16x16x32_bf16 v[108:111], v[154:157], v[196:199], v[108:111]
	v_mfma_f32_16x16x32_bf16 v[104:107], v[162:165], v[196:199], v[104:107]
	v_mfma_f32_16x16x32_bf16 v[92:95], v[154:157], v[210:213], v[92:95]
	v_mfma_f32_16x16x32_bf16 v[88:91], v[162:165], v[210:213], v[88:91]
	v_mfma_f32_16x16x32_bf16 v[76:79], v[154:157], v[218:221], v[76:79]
	v_mfma_f32_16x16x32_bf16 v[72:75], v[162:165], v[218:221], v[72:75]
	v_mfma_f32_16x16x32_bf16 v[116:119], v[166:169], v[184:187], v[116:119]
	v_mfma_f32_16x16x32_bf16 v[112:115], v[176:179], v[184:187], v[112:115]
	v_mfma_f32_16x16x32_bf16 v[100:103], v[166:169], v[192:195], v[100:103]
	v_mfma_f32_16x16x32_bf16 v[96:99], v[176:179], v[192:195], v[96:99]
	v_mfma_f32_16x16x32_bf16 v[84:87], v[166:169], v[202:205], v[84:87]
	v_mfma_f32_16x16x32_bf16 v[80:83], v[176:179], v[202:205], v[80:83]
	v_mfma_f32_16x16x32_bf16 v[68:71], v[166:169], v[214:217], v[68:71]
	v_mfma_f32_16x16x32_bf16 v[64:67], v[176:179], v[214:217], v[64:67]
	v_mfma_f32_16x16x32_bf16 v[116:119], v[170:173], v[188:191], v[116:119]
	v_mfma_f32_16x16x32_bf16 v[112:115], v[180:183], v[188:191], v[112:115]
	v_mfma_f32_16x16x32_bf16 v[100:103], v[170:173], v[196:199], v[100:103]
	v_mfma_f32_16x16x32_bf16 v[96:99], v[180:183], v[196:199], v[96:99]
	v_mfma_f32_16x16x32_bf16 v[84:87], v[170:173], v[210:213], v[84:87]
	v_mfma_f32_16x16x32_bf16 v[80:83], v[180:183], v[210:213], v[80:83]
	v_mfma_f32_16x16x32_bf16 v[68:71], v[170:173], v[218:221], v[68:71]
	v_mfma_f32_16x16x32_bf16 v[64:67], v[180:183], v[218:221], v[64:67]
	s_barrier
	s_add_i32 s59, s54, s67
	v_lshl_add_u64 v[206:207], s[36:37], 0, v[130:131]
	s_mov_b32 m0, s59
	ds_read_b128 v[184:187], v153 offset:16384
	ds_read_b128 v[188:191], v153 offset:17408
	ds_read_b128 v[192:195], v153 offset:18432
	ds_read_b128 v[196:199], v153 offset:19456
	ds_read_b128 v[202:205], v153 offset:20480
	ds_read_b128 v[210:213], v153 offset:21504
	ds_read_b128 v[214:217], v153 offset:22528
	ds_read_b128 v[218:221], v153 offset:23552
	global_load_lds_dwordx4 v[206:207], off
	s_add_i32 m0, s59, 0x2000
	s_add_u32 s70, s36, 0x10000
	v_lshl_add_u64 v[222:223], s[36:37], 0, v[134:135]
	s_addc_u32 s71, s37, 0
	s_add_i32 s59, s55, s67
	global_load_lds_dwordx4 v[222:223], off
	v_lshl_add_u64 v[224:225], s[70:71], 0, v[130:131]
	s_mov_b32 m0, s59
	v_lshl_add_u64 v[226:227], s[38:39], 0, v[132:133]
	global_load_lds_dwordx4 v[224:225], off
	v_lshl_add_u64 v[224:225], s[70:71], 0, v[134:135]
	s_add_i32 m0, s59, 0x2000
	s_nop 0
	global_load_lds_dwordx4 v[224:225], off
	v_lshl_add_u64 v[224:225], s[38:39], 0, v[128:129]
	s_mov_b32 m0, s40
	s_nop 0
	global_load_lds_dwordx4 v[224:225], off
	s_mov_b32 m0, s41
	s_nop 0
	global_load_lds_dwordx4 v[226:227], off
	s_waitcnt vmcnt(8)
	s_waitcnt lgkmcnt(0)
	s_barrier
; #define PG8_STAGE(bufoff, gbase, voff) do { _Pragma("unroll") for (int _i = 0; _i < 2; ++_i) \
;         __builtin_amdgcn_global_load_lds((const unsigned*)((const char*)(gbase) + (voff)[_i]), (PG8_LAS unsigned*)(lds + (bufoff) + ldsw + _i * 8192), 16, 0, 0); } while (0)
; #define PG8_STAGEA(bufoff, gbase, voff) do { _Pragma("unroll") for (int _i = 0; _i < 2; ++_i) \
;         __builtin_amdgcn_global_load_lds((const unsigned*)((const char*)(gbase) + (voff)[_i]), (PG8_LAS unsigned*)(lds + (bufoff) + ldsw + _i * 8192), 16, 0, AUXA); } while (0)
; #define PG8_LDA(dst, b, h) do { _Pragma("unroll") for (int m = 0; m < 4; ++m) _Pragma("unroll") for (int k = 0; k < 2; ++k) dst[m][k] = *(const PG8_LAS bf16x8*)(lds + PG8_SA(b, h) + aoff + m * 2048 + k * 1024); } while (0)
; #define PG8_LDB(dst, b, h) do { _Pragma("unroll") for (int n = 0; n < 2; ++n) _Pragma("unroll") for (int k = 0; k < 2; ++k) dst[n][k] = *(const PG8_LAS bf16x8*)(lds + PG8_SB(b, h) + boff + n * 2048 + k * 1024); } while (0)
; #define PG8_MMA(ai, bj, At, Bt) do { __builtin_amdgcn_s_setprio(1); _Pragma("unroll") for (int m = 0; m < 4; ++m) _Pragma("unroll") for (int n = 0; n < 2; ++n) _Pragma("unroll") for (int k = 0; k < 2; ++k) \
;         acc[ai][bj][m][n] = __builtin_amdgcn_mfma_f32_16x16x32_bf16(Bt[n][k], At[m][k], acc[ai][bj][m][n], 0, 0, 0); __builtin_amdgcn_s_setprio(0); } while (0)
; #define PG8_WAIT_V(n) asm volatile("s_waitcnt vmcnt(" #n ")" ::: "memory")
; #define PG8_WAIT_L(n) asm volatile("s_waitcnt lgkmcnt(" #n ")" ::: "memory")
; #define PG8_BAR __builtin_amdgcn_s_barrier()
; #define PG8_SCHED __builtin_amdgcn_sched_barrier(0)
;     ...
;             PG8_WAIT_V(8); PG8_WAIT_L(0); PG8_BAR; PG8_MMA(1, 0, At, B0); PG8_MMA(1, 1, At, B1); PG8_BAR; PG8_SCHED;
;             PG8_LDB(B0, 1, 0); PG8_LDB(B1, 1, 1); PG8_SCHED; PG8_LDA(At, 1, 0); PG8_STAGEA(PG8_SA(0, 1), a2 + hstep, voffA);
;             PG8_WAIT_V(8); PG8_WAIT_L(0); PG8_BAR; PG8_MMA(0, 0, At, B0); PG8_MMA(0, 1, At, B1); PG8_BAR; PG8_SCHED;
;             PG8_LDA(At, 1, 1); PG8_STAGE(PG8_SB(1, 0), b3, voffB); PG8_STAGE(PG8_SB(1, 1), b3 + hstepB, voffB); PG8_STAGEA(PG8_SA(1, 0), a3, voffA);
	s_waitcnt lgkmcnt(0)
	v_mfma_f32_16x16x32_bf16 v[60:63], v[142:145], v[184:187], v[60:63]
	v_mfma_f32_16x16x32_bf16 v[56:59], v[158:161], v[184:187], v[56:59]
	v_mfma_f32_16x16x32_bf16 v[44:47], v[142:145], v[192:195], v[44:47]
	v_mfma_f32_16x16x32_bf16 v[40:43], v[158:161], v[192:195], v[40:43]
	v_mfma_f32_16x16x32_bf16 v[28:31], v[142:145], v[202:205], v[28:31]
	v_mfma_f32_16x16x32_bf16 v[24:27], v[158:161], v[202:205], v[24:27]
	v_mfma_f32_16x16x32_bf16 v[12:15], v[142:145], v[214:217], v[12:15]
	v_mfma_f32_16x16x32_bf16 v[8:11], v[158:161], v[214:217], v[8:11]
	v_mfma_f32_16x16x32_bf16 v[60:63], v[154:157], v[188:191], v[60:63]
	v_mfma_f32_16x16x32_bf16 v[56:59], v[162:165], v[188:191], v[56:59]
	v_mfma_f32_16x16x32_bf16 v[44:47], v[154:157], v[196:199], v[44:47]
	v_mfma_f32_16x16x32_bf16 v[40:43], v[162:165], v[196:199], v[40:43]
	v_mfma_f32_16x16x32_bf16 v[28:31], v[154:157], v[210:213], v[28:31]
	v_mfma_f32_16x16x32_bf16 v[24:27], v[162:165], v[210:213], v[24:27]
	v_mfma_f32_16x16x32_bf16 v[12:15], v[154:157], v[218:221], v[12:15]
	v_mfma_f32_16x16x32_bf16 v[8:11], v[162:165], v[218:221], v[8:11]
	v_mfma_f32_16x16x32_bf16 v[52:55], v[166:169], v[184:187], v[52:55]
	v_mfma_f32_16x16x32_bf16 v[48:51], v[176:179], v[184:187], v[48:51]
	v_mfma_f32_16x16x32_bf16 v[36:39], v[166:169], v[192:195], v[36:39]
	v_mfma_f32_16x16x32_bf16 v[32:35], v[176:179], v[192:195], v[32:35]
	v_mfma_f32_16x16x32_bf16 v[20:23], v[166:169], v[202:205], v[20:23]
	v_mfma_f32_16x16x32_bf16 v[16:19], v[176:179], v[202:205], v[16:19]
	v_mfma_f32_16x16x32_bf16 v[4:7], v[166:169], v[214:217], v[4:7]
	v_mfma_f32_16x16x32_bf16 v[0:3], v[176:179], v[214:217], v[0:3]
	v_mfma_f32_16x16x32_bf16 v[52:55], v[170:173], v[188:191], v[52:55]
	v_mfma_f32_16x16x32_bf16 v[48:51], v[180:183], v[188:191], v[48:51]
	v_mfma_f32_16x16x32_bf16 v[36:39], v[170:173], v[196:199], v[36:39]
	v_mfma_f32_16x16x32_bf16 v[32:35], v[180:183], v[196:199], v[32:35]
	v_mfma_f32_16x16x32_bf16 v[20:23], v[170:173], v[210:213], v[20:23]
	v_mfma_f32_16x16x32_bf16 v[16:19], v[180:183], v[210:213], v[16:19]
	v_mfma_f32_16x16x32_bf16 v[4:7], v[170:173], v[218:221], v[4:7]
	v_mfma_f32_16x16x32_bf16 v[0:3], v[180:183], v[218:221], v[0:3]
	s_barrier
	s_add_i32 s59, 0, 0x18000
	s_add_i32 s70, 0, 0x1c000
	v_add_u32_e32 v162, s59, v147
	v_add_u32_e32 v174, s70, v147
	ds_read_b128 v[142:145], v162
	ds_read_b128 v[154:157], v162 offset:1024
	ds_read_b128 v[158:161], v162 offset:2048
	ds_read_b128 v[162:165], v162 offset:3072
	ds_read_b128 v[166:169], v174
	ds_read_b128 v[170:173], v174 offset:1024
	ds_read_b128 v[176:179], v174 offset:2048
	ds_read_b128 v[180:183], v174 offset:3072
	s_add_u32 s38, s38, 0x40000
	s_addc_u32 s39, s39, 0
	s_mov_b32 m0, s43
	v_lshl_add_u64 v[228:229], s[38:39], 0, v[128:129]
	ds_read_b128 v[184:187], v153 offset:32768
	ds_read_b128 v[188:191], v153 offset:33792
	ds_read_b128 v[192:195], v153 offset:34816
	ds_read_b128 v[196:199], v153 offset:35840
	ds_read_b128 v[202:205], v153 offset:36864
	ds_read_b128 v[210:213], v153 offset:37888
	ds_read_b128 v[214:217], v153 offset:38912
	ds_read_b128 v[218:221], v153 offset:39936
	global_load_lds_dwordx4 v[228:229], off
	v_lshl_add_u64 v[228:229], s[38:39], 0, v[132:133]
	s_mov_b32 m0, s44
	s_nop 0
	global_load_lds_dwordx4 v[228:229], off
	s_waitcnt vmcnt(8)
	s_waitcnt lgkmcnt(0)
	s_barrier
	s_waitcnt lgkmcnt(0)
	v_mfma_f32_16x16x32_bf16 v[124:127], v[142:145], v[184:187], v[124:127]
	v_mfma_f32_16x16x32_bf16 v[120:123], v[158:161], v[184:187], v[120:123]
	v_mfma_f32_16x16x32_bf16 v[108:111], v[142:145], v[192:195], v[108:111]
	v_mfma_f32_16x16x32_bf16 v[104:107], v[158:161], v[192:195], v[104:107]
	v_mfma_f32_16x16x32_bf16 v[92:95], v[142:145], v[202:205], v[92:95]
	v_mfma_f32_16x16x32_bf16 v[88:91], v[158:161], v[202:205], v[88:91]
	v_mfma_f32_16x16x32_bf16 v[76:79], v[142:145], v[214:217], v[76:79]
	v_mfma_f32_16x16x32_bf16 v[72:75], v[158:161], v[214:217], v[72:75]
	v_mfma_f32_16x16x32_bf16 v[124:127], v[154:157], v[188:191], v[124:127]
	v_mfma_f32_16x16x32_bf16 v[120:123], v[162:165], v[188:191], v[120:123]
	v_mfma_f32_16x16x32_bf16 v[108:111], v[154:157], v[196:199], v[108:111]
	v_mfma_f32_16x16x32_bf16 v[104:107], v[162:165], v[196:199], v[104:107]
	v_mfma_f32_16x16x32_bf16 v[92:95], v[154:157], v[210:213], v[92:95]
	v_mfma_f32_16x16x32_bf16 v[88:91], v[162:165], v[210:213], v[88:91]
	v_mfma_f32_16x16x32_bf16 v[76:79], v[154:157], v[218:221], v[76:79]
	v_mfma_f32_16x16x32_bf16 v[72:75], v[162:165], v[218:221], v[72:75]
	v_mfma_f32_16x16x32_bf16 v[116:119], v[166:169], v[184:187], v[116:119]
	v_mfma_f32_16x16x32_bf16 v[112:115], v[176:179], v[184:187], v[112:115]
	v_mfma_f32_16x16x32_bf16 v[100:103], v[166:169], v[192:195], v[100:103]
	v_mfma_f32_16x16x32_bf16 v[96:99], v[176:179], v[192:195], v[96:99]
	v_mfma_f32_16x16x32_bf16 v[84:87], v[166:169], v[202:205], v[84:87]
	v_mfma_f32_16x16x32_bf16 v[80:83], v[176:179], v[202:205], v[80:83]
	v_mfma_f32_16x16x32_bf16 v[68:71], v[166:169], v[214:217], v[68:71]
	v_mfma_f32_16x16x32_bf16 v[64:67], v[176:179], v[214:217], v[64:67]
	v_mfma_f32_16x16x32_bf16 v[116:119], v[170:173], v[188:191], v[116:119]
	v_mfma_f32_16x16x32_bf16 v[112:115], v[180:183], v[188:191], v[112:115]
	v_mfma_f32_16x16x32_bf16 v[100:103], v[170:173], v[196:199], v[100:103]
	v_mfma_f32_16x16x32_bf16 v[96:99], v[180:183], v[196:199], v[96:99]
	v_mfma_f32_16x16x32_bf16 v[84:87], v[170:173], v[210:213], v[84:87]
	v_mfma_f32_16x16x32_bf16 v[80:83], v[180:183], v[210:213], v[80:83]
	v_mfma_f32_16x16x32_bf16 v[68:71], v[170:173], v[218:221], v[68:71]
	v_mfma_f32_16x16x32_bf16 v[64:67], v[180:183], v[218:221], v[64:67]
	s_barrier
; #define PG8_STAGE(bufoff, gbase, voff) do { _Pragma("unroll") for (int _i = 0; _i < 2; ++_i) \
;         __builtin_amdgcn_global_load_lds((const unsigned*)((const char*)(gbase) + (voff)[_i]), (PG8_LAS unsigned*)(lds + (bufoff) + ldsw + _i * 8192), 16, 0, 0); } while (0)
; #define PG8_STAGEA(bufoff, gbase, voff) do { _Pragma("unroll") for (int _i = 0; _i < 2; ++_i) \
;         __builtin_amdgcn_global_load_lds((const unsigned*)((const char*)(gbase) + (voff)[_i]), (PG8_LAS unsigned*)(lds + (bufoff) + ldsw + _i * 8192), 16, 0, AUXA); } while (0)
; #define PG8_LDA(dst, b, h) do { _Pragma("unroll") for (int m = 0; m < 4; ++m) _Pragma("unroll") for (int k = 0; k < 2; ++k) dst[m][k] = *(const PG8_LAS bf16x8*)(lds + PG8_SA(b, h) + aoff + m * 2048 + k * 1024); } while (0)
; #define PG8_MMA(ai, bj, At, Bt) do { __builtin_amdgcn_s_setprio(1); _Pragma("unroll") for (int m = 0; m < 4; ++m) _Pragma("unroll") for (int n = 0; n < 2; ++n) _Pragma("unroll") for (int k = 0; k < 2; ++k) \
;         acc[ai][bj][m][n] = __builtin_amdgcn_mfma_f32_16x16x32_bf16(Bt[n][k], At[m][k], acc[ai][bj][m][n], 0, 0, 0); __builtin_amdgcn_s_setprio(0); } while (0)
; #define PG8_WAIT_V(n) asm volatile("s_waitcnt vmcnt(" #n ")" ::: "memory")
; #define PG8_WAIT_L(n) asm volatile("s_waitcnt lgkmcnt(" #n ")" ::: "memory")
; #define PG8_BAR __builtin_amdgcn_s_barrier()
; #define PG8_SCHED __builtin_amdgcn_sched_barrier(0)
;     ...
;         for (int t = 0; t < nt; t += 2) {
;     ...
;             PG8_LDA(At, 1, 1); PG8_STAGE(PG8_SB(1, 0), b3, voffB); PG8_STAGE(PG8_SB(1, 1), b3 + hstepB, voffB); PG8_STAGEA(PG8_SA(1, 0), a3, voffA);
;             PG8_WAIT_V(8); PG8_WAIT_L(0); PG8_BAR; PG8_MMA(1, 0, At, B0); PG8_MMA(1, 1, At, B1); PG8_BAR; PG8_SCHED;
	s_add_i32 s38, s59, s67
	v_lshl_add_u64 v[206:207], v[206:207], 0, s[18:19]
	s_mov_b32 m0, s38
	ds_read_b128 v[184:187], v153 offset:49152
	ds_read_b128 v[188:191], v153 offset:50176
	ds_read_b128 v[192:195], v153 offset:51200
	ds_read_b128 v[196:199], v153 offset:52224
	ds_read_b128 v[202:205], v153 offset:53248
	ds_read_b128 v[210:213], v153 offset:54272
	ds_read_b128 v[214:217], v153 offset:55296
	ds_read_b128 v[218:221], v153 offset:56320
	global_load_lds_dwordx4 v[206:207], off
	s_add_i32 m0, s38, 0x2000
	s_add_u32 s36, s36, 0x10080
	v_lshl_add_u64 v[206:207], v[222:223], 0, s[18:19]
	s_addc_u32 s37, s37, 0
	s_add_i32 s38, s70, s67
	global_load_lds_dwordx4 v[206:207], off
	v_lshl_add_u64 v[206:207], s[36:37], 0, v[130:131]
	s_mov_b32 m0, s38
	s_nop 0
	global_load_lds_dwordx4 v[206:207], off
	v_lshl_add_u64 v[206:207], s[36:37], 0, v[134:135]
	s_add_i32 m0, s38, 0x2000
	s_nop 0
	global_load_lds_dwordx4 v[206:207], off
	v_lshl_add_u64 v[206:207], v[224:225], 0, s[18:19]
	s_mov_b32 m0, s45
	s_nop 0
	global_load_lds_dwordx4 v[206:207], off
	v_lshl_add_u64 v[206:207], v[226:227], 0, s[18:19]
	s_mov_b32 m0, s46
	s_nop 0
	global_load_lds_dwordx4 v[206:207], off
	s_waitcnt vmcnt(8)
	s_waitcnt lgkmcnt(0)
	s_barrier
	s_waitcnt lgkmcnt(0)
	v_mfma_f32_16x16x32_bf16 v[60:63], v[142:145], v[184:187], v[60:63]
	v_mfma_f32_16x16x32_bf16 v[56:59], v[158:161], v[184:187], v[56:59]
	v_mfma_f32_16x16x32_bf16 v[44:47], v[142:145], v[192:195], v[44:47]
	v_mfma_f32_16x16x32_bf16 v[40:43], v[158:161], v[192:195], v[40:43]
	v_mfma_f32_16x16x32_bf16 v[28:31], v[142:145], v[202:205], v[28:31]
	v_mfma_f32_16x16x32_bf16 v[24:27], v[158:161], v[202:205], v[24:27]
	v_mfma_f32_16x16x32_bf16 v[12:15], v[142:145], v[214:217], v[12:15]
	v_mfma_f32_16x16x32_bf16 v[8:11], v[158:161], v[214:217], v[8:11]
	v_mfma_f32_16x16x32_bf16 v[60:63], v[154:157], v[188:191], v[60:63]
	v_mfma_f32_16x16x32_bf16 v[56:59], v[162:165], v[188:191], v[56:59]
	v_mfma_f32_16x16x32_bf16 v[44:47], v[154:157], v[196:199], v[44:47]
	v_mfma_f32_16x16x32_bf16 v[40:43], v[162:165], v[196:199], v[40:43]
	v_mfma_f32_16x16x32_bf16 v[28:31], v[154:157], v[210:213], v[28:31]
	v_mfma_f32_16x16x32_bf16 v[24:27], v[162:165], v[210:213], v[24:27]
	v_mfma_f32_16x16x32_bf16 v[12:15], v[154:157], v[218:221], v[12:15]
	v_mfma_f32_16x16x32_bf16 v[8:11], v[162:165], v[218:221], v[8:11]
	v_mfma_f32_16x16x32_bf16 v[52:55], v[166:169], v[184:187], v[52:55]
	v_mfma_f32_16x16x32_bf16 v[48:51], v[176:179], v[184:187], v[48:51]
	v_mfma_f32_16x16x32_bf16 v[36:39], v[166:169], v[192:195], v[36:39]
	v_mfma_f32_16x16x32_bf16 v[32:35], v[176:179], v[192:195], v[32:35]
	v_mfma_f32_16x16x32_bf16 v[20:23], v[166:169], v[202:205], v[20:23]
	v_mfma_f32_16x16x32_bf16 v[16:19], v[176:179], v[202:205], v[16:19]
	v_mfma_f32_16x16x32_bf16 v[4:7], v[166:169], v[214:217], v[4:7]
	v_mfma_f32_16x16x32_bf16 v[0:3], v[176:179], v[214:217], v[0:3]
	v_mfma_f32_16x16x32_bf16 v[52:55], v[170:173], v[188:191], v[52:55]
	v_mfma_f32_16x16x32_bf16 v[48:51], v[180:183], v[188:191], v[48:51]
	v_mfma_f32_16x16x32_bf16 v[36:39], v[170:173], v[196:199], v[36:39]
	v_mfma_f32_16x16x32_bf16 v[32:35], v[180:183], v[196:199], v[32:35]
	v_mfma_f32_16x16x32_bf16 v[20:23], v[170:173], v[210:213], v[20:23]
	v_mfma_f32_16x16x32_bf16 v[16:19], v[180:183], v[210:213], v[16:19]
	v_mfma_f32_16x16x32_bf16 v[4:7], v[170:173], v[218:221], v[4:7]
	v_mfma_f32_16x16x32_bf16 v[0:3], v[180:183], v[218:221], v[0:3]
	s_barrier
	s_add_i32 s58, s58, 2
	s_add_u32 s34, s34, 0x100
	s_addc_u32 s35, s35, 0
	s_add_u32 s56, s56, 0x100
	s_addc_u32 s57, s57, 0
	s_cmp_gt_u32 s58, 13
	s_cbranch_scc0 .LBB0_854
	s_setprio 0
	s_and_b64 vcc, exec, s[20:21]
	s_cbranch_vccz .LBB0_857
	s_barrier
